# GEMM epilogue stores (in-proj, gates, up) plain write-back instead of sc1 write-through: the next unit's counted vmcnt waits no longer sit behind write-through acks
# speedup vs baseline: 1.0096x; 1.0043x over previous
; __device__ __forceinline__ unsigned pk2_(float lo, float hi) { f32x2_t v = {lo, hi}; bf16x2_t b = __builtin_convertvector(v, bf16x2_t); return __builtin_bit_cast(unsigned, b); }
; __device__ __forceinline__ float sigm(float x) { return __builtin_amdgcn_rcpf(1.0f + __expf(-x)); }
; __device__ __forceinline__ void store16_wt(void* p, u32x4 v) { asm volatile("global_store_dwordx4 %0, %1, off sc1\n\ts_nop 1" :: "v"(p), "v"(v) : "memory"); }
; __device__ __forceinline__ float sigm(float x) { return __builtin_amdgcn_rcpf(1.0f + __expf(-x)); }
;     __device__ __forceinline__ void operator()(const f32x4 (&acc)[2][2][4][2], const Unit& u, int wr, int wc, int fr, int fq) const {
;         const int c0 = wc * 32 + 8 * fq;
; #pragma unroll
;         for (int ai = 0; ai < 2; ++ai)
; #pragma unroll
;             for (int m = 0; m < 4; ++m) { bf16_t* rowp = gm.at(u.pm, wr * 64 + fr + ai * HALF + m * 16, u.pn, c0);
; #pragma unroll
;                 for (int bj = 0; bj < 2; ++bj) { const f32x4 v0 = acc[ai][bj][m][0], v1 = acc[ai][bj][m][1];
;                     u32x4 w; w.x = pk2_(sigm(v0[0]), sigm(v0[1])); w.y = pk2_(sigm(v0[2]), sigm(v0[3])); w.z = pk2_(sigm(v1[0]), sigm(v1[1])); w.w = pk2_(sigm(v1[2]), sigm(v1[3]));
;                     store16_wt(rowp + bj * HALF, w); } }
;     }
.LBB0_1143:
	s_lshl_b32 s9, s4, 8
	s_lshl_b32 s46, s14, 8
	s_add_i32 s5, s9, 0xffffc000
	s_add_i32 s96, s46, 0xfffff400
	s_ashr_i32 s47, s46, 31
	s_cmp_lt_i32 s4, 64
	s_cselect_b32 s11, s9, s5
	s_cselect_b32 s5, s3, s21
	s_cselect_b32 s4, s17, s29
	s_cmp_lt_i32 s14, 12
	s_cselect_b64 vcc, -1, 0
	v_mul_f32_e32 v122, 0xbfb8aa3b, v122
	s_and_b64 s[12:13], vcc, exec
	v_exp_f32_e32 v122, v122
	v_mul_f32_e32 v123, 0xbfb8aa3b, v123
	s_cselect_b32 s15, s9, s11
	s_cselect_b32 s84, s18, s4
	s_cselect_b32 s85, s19, s5
	v_exp_f32_e32 v123, v123
	s_cselect_b32 s36, s34, 0x1800
	v_add_u32_e32 v143, s15, v17
	v_mov_b64_e32 v[154:155], s[84:85]
	s_cselect_b32 s12, s46, s96
	s_cselect_b32 s13, s47, 0
	s_cmp_gt_i32 s14, 11
	v_mad_i64_i32 v[154:155], s[14:15], s36, v143, v[154:155]
	v_mul_f32_e32 v126, 0xbfb8aa3b, v126
	v_lshl_add_u64 v[154:155], s[12:13], 1, v[154:155]
	v_mov_b32_e32 v143, v16
	v_exp_f32_e32 v153, v126
	v_mul_f32_e32 v126, 0xbfb8aa3b, v127
	v_add_f32_e32 v122, 1.0, v122
	v_exp_f32_e32 v156, v126
	v_lshl_add_u64 v[126:127], v[154:155], 0, v[142:143]
	v_rcp_f32_e32 v155, v122
	v_add_f32_e32 v122, 1.0, v123
	v_mul_f32_e32 v123, 0xbfb8aa3b, v124
	v_mul_f32_e32 v128, 0xbfb8aa3b, v128
	v_mul_f32_e32 v129, 0xbfb8aa3b, v129
	v_exp_f32_e32 v123, v123
	v_mul_f32_e32 v124, 0xbfb8aa3b, v125
	v_exp_f32_e32 v128, v128
	v_exp_f32_e32 v129, v129
	v_exp_f32_e32 v124, v124
	v_add_f32_e32 v153, 1.0, v153
	v_add_f32_e32 v154, 1.0, v156
	v_rcp_f32_e32 v125, v122
	v_add_f32_e32 v122, 1.0, v123
	v_mul_f32_e32 v114, 0xbfb8aa3b, v114
	v_rcp_f32_e32 v153, v153
	v_rcp_f32_e32 v154, v154
	v_add_f32_e32 v128, 1.0, v128
	v_add_f32_e32 v129, 1.0, v129
	v_rcp_f32_e32 v156, v122
	v_add_f32_e32 v122, 1.0, v124
	v_exp_f32_e32 v114, v114
	v_mul_f32_e32 v115, 0xbfb8aa3b, v115
	v_rcp_f32_e32 v128, v128
	v_rcp_f32_e32 v129, v129
	v_rcp_f32_e32 v157, v122
	v_exp_f32_e32 v115, v115
	v_cvt_pk_bf16_f32 v122, v153, v154
	v_add_f32_e32 v114, 1.0, v114
	v_cvt_pk_bf16_f32 v123, v128, v129
	v_cvt_pk_bf16_f32 v124, v155, v125
	v_cvt_pk_bf16_f32 v125, v156, v157
	global_store_dwordx4 v[126:127], v[122:125], off
	s_nop 1
	v_rcp_f32_e32 v122, v114
	v_add_f32_e32 v114, 1.0, v115
	v_mul_f32_e32 v115, 0xbfb8aa3b, v116
	v_mul_f32_e32 v118, 0xbfb8aa3b, v118
	v_mul_f32_e32 v119, 0xbfb8aa3b, v119
	v_mul_f32_e32 v120, 0xbfb8aa3b, v120
	v_mul_f32_e32 v121, 0xbfb8aa3b, v121
	v_exp_f32_e32 v115, v115
	v_mul_f32_e32 v116, 0xbfb8aa3b, v117
	v_exp_f32_e32 v118, v118
	v_exp_f32_e32 v119, v119
	v_exp_f32_e32 v120, v120
	v_exp_f32_e32 v121, v121
	v_exp_f32_e32 v116, v116
	v_rcp_f32_e32 v117, v114
	v_add_f32_e32 v114, 1.0, v115
	v_add_f32_e32 v118, 1.0, v118
	v_add_f32_e32 v119, 1.0, v119
	v_add_f32_e32 v120, 1.0, v120
	v_add_f32_e32 v121, 1.0, v121
	v_rcp_f32_e32 v123, v114
	v_add_f32_e32 v114, 1.0, v116
	v_rcp_f32_e32 v118, v118
	v_rcp_f32_e32 v119, v119
	v_rcp_f32_e32 v120, v120
	v_rcp_f32_e32 v121, v121
	v_rcp_f32_e32 v124, v114
	v_cvt_pk_bf16_f32 v114, v118, v119
	v_cvt_pk_bf16_f32 v116, v122, v117
	v_cvt_pk_bf16_f32 v115, v120, v121
	v_cvt_pk_bf16_f32 v117, v123, v124
	v_lshl_add_u64 v[118:119], v[126:127], 0, s[64:65]
	global_store_dwordx4 v[118:119], v[114:117], off
	s_nop 1
	s_mov_b64 s[12:13], 0x1800
	s_mov_b64 s[68:69], s[96:97]
	s_mov_b32 s13, s11
	s_mov_b64 s[36:37], 0x1800
	s_mov_b64 s[76:77], s[4:5]
	s_mov_b64 s[14:15], s[96:97]
	s_cbranch_scc1 .LBB0_1145
	s_mov_b64 s[36:37], 0x4200
	s_mov_b32 s13, s9
	s_mov_b64 s[76:77], s[18:19]
	s_mov_b64 s[14:15], s[46:47]
.LBB0_1145:
	v_mul_f32_e32 v106, 0xbfb8aa3b, v106
	v_add_u32_e32 v116, s13, v145
	v_mov_b64_e32 v[114:115], s[76:77]
	v_mul_f32_e32 v110, 0xbfb8aa3b, v110
	v_exp_f32_e32 v106, v106
	v_mul_f32_e32 v107, 0xbfb8aa3b, v107
	v_mad_i64_i32 v[114:115], s[74:75], s36, v116, v[114:115]
	v_exp_f32_e32 v116, v110
	v_exp_f32_e32 v107, v107
	s_lshl_b64 s[14:15], s[14:15], 1
	v_lshl_add_u64 v[114:115], v[114:115], 0, s[14:15]
	v_mul_f32_e32 v110, 0xbfb8aa3b, v111
	v_add_f32_e32 v106, 1.0, v106
	v_exp_f32_e32 v117, v110
	v_lshl_add_u64 v[110:111], v[114:115], 0, v[142:143]
	v_add_f32_e32 v114, 1.0, v116
	v_rcp_f32_e32 v116, v106
	v_add_f32_e32 v106, 1.0, v107
	v_mul_f32_e32 v107, 0xbfb8aa3b, v108
	v_mul_f32_e32 v112, 0xbfb8aa3b, v112
	v_mul_f32_e32 v113, 0xbfb8aa3b, v113
	v_exp_f32_e32 v107, v107
	v_mul_f32_e32 v108, 0xbfb8aa3b, v109
	v_exp_f32_e32 v112, v112
	v_exp_f32_e32 v113, v113
	v_exp_f32_e32 v108, v108
	v_add_f32_e32 v115, 1.0, v117
	v_rcp_f32_e32 v109, v106
	v_add_f32_e32 v106, 1.0, v107
	v_mul_f32_e32 v98, 0xbfb8aa3b, v98
	v_rcp_f32_e32 v114, v114
	v_rcp_f32_e32 v115, v115
	v_add_f32_e32 v112, 1.0, v112
	v_add_f32_e32 v113, 1.0, v113
	v_rcp_f32_e32 v117, v106
	v_add_f32_e32 v106, 1.0, v108
	v_exp_f32_e32 v98, v98
	v_mul_f32_e32 v99, 0xbfb8aa3b, v99
	v_rcp_f32_e32 v112, v112
	v_rcp_f32_e32 v113, v113
	v_rcp_f32_e32 v118, v106
	v_exp_f32_e32 v99, v99
	v_cvt_pk_bf16_f32 v106, v114, v115
	v_add_f32_e32 v98, 1.0, v98
	v_cvt_pk_bf16_f32 v107, v112, v113
	v_cvt_pk_bf16_f32 v108, v116, v109
	v_cvt_pk_bf16_f32 v109, v117, v118
	v_mul_f32_e32 v102, 0xbfb8aa3b, v102
	v_mul_f32_e32 v103, 0xbfb8aa3b, v103
	global_store_dwordx4 v[110:111], v[106:109], off
	s_nop 1
	v_mul_f32_e32 v104, 0xbfb8aa3b, v104
	v_mul_f32_e32 v105, 0xbfb8aa3b, v105
	v_rcp_f32_e32 v106, v98
	v_add_f32_e32 v98, 1.0, v99
	v_mul_f32_e32 v99, 0xbfb8aa3b, v100
	v_exp_f32_e32 v102, v102
	v_exp_f32_e32 v103, v103
	v_exp_f32_e32 v104, v104
	v_exp_f32_e32 v105, v105
	v_exp_f32_e32 v99, v99
	v_mul_f32_e32 v100, 0xbfb8aa3b, v101
	v_exp_f32_e32 v100, v100
	v_add_f32_e32 v102, 1.0, v102
	v_add_f32_e32 v103, 1.0, v103
	v_add_f32_e32 v104, 1.0, v104
	v_add_f32_e32 v105, 1.0, v105
	v_rcp_f32_e32 v101, v98
; __device__ __forceinline__ unsigned pk2_(float lo, float hi) { f32x2_t v = {lo, hi}; bf16x2_t b = __builtin_convertvector(v, bf16x2_t); return __builtin_bit_cast(unsigned, b); }
; __device__ __forceinline__ float sigm(float x) { return __builtin_amdgcn_rcpf(1.0f + __expf(-x)); }
; __device__ __forceinline__ void store16_wt(void* p, u32x4 v) { asm volatile("global_store_dwordx4 %0, %1, off sc1\n\ts_nop 1" :: "v"(p), "v"(v) : "memory"); }
; __device__ __forceinline__ float sigm(float x) { return __builtin_amdgcn_rcpf(1.0f + __expf(-x)); }
;     __device__ __forceinline__ void operator()(const f32x4 (&acc)[2][2][4][2], const Unit& u, int wr, int wc, int fr, int fq) const {
;         const int c0 = wc * 32 + 8 * fq;
; #pragma unroll
;         for (int ai = 0; ai < 2; ++ai)
; #pragma unroll
;             for (int m = 0; m < 4; ++m) { bf16_t* rowp = gm.at(u.pm, wr * 64 + fr + ai * HALF + m * 16, u.pn, c0);
; #pragma unroll
;                 for (int bj = 0; bj < 2; ++bj) { const f32x4 v0 = acc[ai][bj][m][0], v1 = acc[ai][bj][m][1];
;                     u32x4 w; w.x = pk2_(sigm(v0[0]), sigm(v0[1])); w.y = pk2_(sigm(v0[2]), sigm(v0[3])); w.z = pk2_(sigm(v1[0]), sigm(v1[1])); w.w = pk2_(sigm(v1[2]), sigm(v1[3]));
;                     store16_wt(rowp + bj * HALF, w); } }
;     }
	v_add_f32_e32 v98, 1.0, v99
	v_rcp_f32_e32 v102, v102
	v_rcp_f32_e32 v103, v103
	v_rcp_f32_e32 v104, v104
	v_rcp_f32_e32 v105, v105
	v_rcp_f32_e32 v107, v98
	v_add_f32_e32 v98, 1.0, v100
	v_rcp_f32_e32 v108, v98
	v_cvt_pk_bf16_f32 v98, v102, v103
	v_cvt_pk_bf16_f32 v99, v104, v105
	v_cvt_pk_bf16_f32 v100, v106, v101
	v_mul_f32_e32 v90, 0xbfb8aa3b, v90
	v_cvt_pk_bf16_f32 v101, v107, v108
	v_lshl_add_u64 v[102:103], v[110:111], 0, s[64:65]
	global_store_dwordx4 v[102:103], v[98:101], off
	s_nop 1
	v_add_u32_e32 v100, s13, v146
	v_mov_b64_e32 v[98:99], s[84:85]
	v_mul_f32_e32 v94, 0xbfb8aa3b, v94
	v_exp_f32_e32 v90, v90
	v_mul_f32_e32 v91, 0xbfb8aa3b, v91
	v_mad_i64_i32 v[98:99], s[36:37], s36, v100, v[98:99]
	v_exp_f32_e32 v100, v94
	v_exp_f32_e32 v91, v91
	v_lshl_add_u64 v[98:99], v[98:99], 0, s[14:15]
	v_mul_f32_e32 v94, 0xbfb8aa3b, v95
	v_add_f32_e32 v90, 1.0, v90
	v_exp_f32_e32 v101, v94
	v_lshl_add_u64 v[94:95], v[98:99], 0, v[142:143]
	v_add_f32_e32 v98, 1.0, v100
	v_rcp_f32_e32 v100, v90
	v_add_f32_e32 v90, 1.0, v91
	v_mul_f32_e32 v91, 0xbfb8aa3b, v92
	v_mul_f32_e32 v96, 0xbfb8aa3b, v96
	v_mul_f32_e32 v97, 0xbfb8aa3b, v97
	v_exp_f32_e32 v91, v91
	v_mul_f32_e32 v92, 0xbfb8aa3b, v93
	v_exp_f32_e32 v96, v96
	v_exp_f32_e32 v97, v97
	v_exp_f32_e32 v92, v92
	v_add_f32_e32 v99, 1.0, v101
	v_rcp_f32_e32 v93, v90
	v_add_f32_e32 v90, 1.0, v91
	v_mul_f32_e32 v82, 0xbfb8aa3b, v82
	v_rcp_f32_e32 v98, v98
	v_rcp_f32_e32 v99, v99
	v_add_f32_e32 v96, 1.0, v96
	v_add_f32_e32 v97, 1.0, v97
	v_rcp_f32_e32 v101, v90
	v_add_f32_e32 v90, 1.0, v92
	v_exp_f32_e32 v82, v82
	v_mul_f32_e32 v83, 0xbfb8aa3b, v83
	v_rcp_f32_e32 v96, v96
	v_rcp_f32_e32 v97, v97
	v_rcp_f32_e32 v102, v90
	v_exp_f32_e32 v83, v83
	v_cvt_pk_bf16_f32 v90, v98, v99
	v_add_f32_e32 v82, 1.0, v82
	v_cvt_pk_bf16_f32 v91, v96, v97
	v_cvt_pk_bf16_f32 v92, v100, v93
	v_cvt_pk_bf16_f32 v93, v101, v102
	global_store_dwordx4 v[94:95], v[90:93], off
	s_nop 1
	v_rcp_f32_e32 v90, v82
	v_add_f32_e32 v82, 1.0, v83
	v_mul_f32_e32 v83, 0xbfb8aa3b, v84
	v_mul_f32_e32 v86, 0xbfb8aa3b, v86
	v_mul_f32_e32 v87, 0xbfb8aa3b, v87
	v_mul_f32_e32 v88, 0xbfb8aa3b, v88
	v_mul_f32_e32 v89, 0xbfb8aa3b, v89
	v_exp_f32_e32 v83, v83
	v_mul_f32_e32 v84, 0xbfb8aa3b, v85
	v_exp_f32_e32 v86, v86
	v_exp_f32_e32 v87, v87
	v_exp_f32_e32 v88, v88
	v_exp_f32_e32 v89, v89
	v_exp_f32_e32 v84, v84
	v_rcp_f32_e32 v85, v82
	v_add_f32_e32 v82, 1.0, v83
	v_add_f32_e32 v86, 1.0, v86
	v_add_f32_e32 v87, 1.0, v87
	v_add_f32_e32 v88, 1.0, v88
	v_add_f32_e32 v89, 1.0, v89
	v_rcp_f32_e32 v91, v82
	v_add_f32_e32 v82, 1.0, v84
	v_rcp_f32_e32 v86, v86
	v_rcp_f32_e32 v87, v87
	v_rcp_f32_e32 v88, v88
	v_rcp_f32_e32 v89, v89
	v_rcp_f32_e32 v92, v82
	v_cvt_pk_bf16_f32 v82, v86, v87
	v_cvt_pk_bf16_f32 v84, v90, v85
	v_cvt_pk_bf16_f32 v83, v88, v89
	v_cvt_pk_bf16_f32 v85, v91, v92
	v_lshl_add_u64 v[86:87], v[94:95], 0, s[64:65]
	global_store_dwordx4 v[86:87], v[82:85], off
	s_nop 1
	v_cndmask_b32_e64 v82, 0, 1, vcc
	v_cmp_ne_u32_e64 s[36:37], 1, v82
	s_andn2_b64 vcc, exec, vcc
	s_mov_b32 s13, s11
	s_mov_b64 s[76:77], s[4:5]
	s_mov_b64 s[14:15], s[68:69]
	s_cbranch_vccnz .LBB0_1147
	s_mov_b64 s[12:13], 0x4200
	s_mov_b32 s13, s9
	s_mov_b64 s[76:77], s[18:19]
	s_mov_b64 s[14:15], s[46:47]
.LBB0_1147:
	v_mul_f32_e32 v74, 0xbfb8aa3b, v74
	v_add_u32_e32 v84, s13, v147
	v_mov_b64_e32 v[82:83], s[76:77]
	v_mul_f32_e32 v78, 0xbfb8aa3b, v78
	v_exp_f32_e32 v74, v74
	v_mul_f32_e32 v75, 0xbfb8aa3b, v75
	v_mad_i64_i32 v[82:83], s[74:75], s12, v84, v[82:83]
	v_exp_f32_e32 v84, v78
	v_exp_f32_e32 v75, v75
	s_lshl_b64 s[14:15], s[14:15], 1
	v_lshl_add_u64 v[82:83], v[82:83], 0, s[14:15]
	v_mov_b32_e32 v143, v16
	v_mul_f32_e32 v78, 0xbfb8aa3b, v79
	v_add_f32_e32 v74, 1.0, v74
	v_exp_f32_e32 v85, v78
	v_lshl_add_u64 v[78:79], v[82:83], 0, v[142:143]
	v_add_f32_e32 v82, 1.0, v84
	v_rcp_f32_e32 v84, v74
	v_add_f32_e32 v74, 1.0, v75
	v_mul_f32_e32 v75, 0xbfb8aa3b, v76
	v_mul_f32_e32 v80, 0xbfb8aa3b, v80
	v_mul_f32_e32 v81, 0xbfb8aa3b, v81
	v_exp_f32_e32 v75, v75
	v_mul_f32_e32 v76, 0xbfb8aa3b, v77
	v_exp_f32_e32 v80, v80
	v_exp_f32_e32 v81, v81
	v_exp_f32_e32 v76, v76
	v_add_f32_e32 v83, 1.0, v85
	v_rcp_f32_e32 v77, v74
	v_add_f32_e32 v74, 1.0, v75
	v_mul_f32_e32 v66, 0xbfb8aa3b, v66
	v_rcp_f32_e32 v82, v82
	v_rcp_f32_e32 v83, v83
	v_add_f32_e32 v80, 1.0, v80
	v_add_f32_e32 v81, 1.0, v81
	v_rcp_f32_e32 v85, v74
	v_add_f32_e32 v74, 1.0, v76
	v_exp_f32_e32 v66, v66
	v_mul_f32_e32 v67, 0xbfb8aa3b, v67
	v_rcp_f32_e32 v80, v80
	v_rcp_f32_e32 v81, v81
	v_rcp_f32_e32 v86, v74
	v_exp_f32_e32 v67, v67
	v_cvt_pk_bf16_f32 v74, v82, v83
	v_add_f32_e32 v66, 1.0, v66
	v_cvt_pk_bf16_f32 v75, v80, v81
	v_cvt_pk_bf16_f32 v76, v84, v77
	v_cvt_pk_bf16_f32 v77, v85, v86
	v_mul_f32_e32 v70, 0xbfb8aa3b, v70
	v_mul_f32_e32 v71, 0xbfb8aa3b, v71
	global_store_dwordx4 v[78:79], v[74:77], off
	s_nop 1
	v_mul_f32_e32 v72, 0xbfb8aa3b, v72
	v_mul_f32_e32 v73, 0xbfb8aa3b, v73
	v_rcp_f32_e32 v74, v66
	v_add_f32_e32 v66, 1.0, v67
	v_mul_f32_e32 v67, 0xbfb8aa3b, v68
	v_exp_f32_e32 v70, v70
	v_exp_f32_e32 v71, v71
	v_exp_f32_e32 v72, v72
	v_exp_f32_e32 v73, v73
	v_exp_f32_e32 v67, v67
	v_mul_f32_e32 v68, 0xbfb8aa3b, v69
	v_exp_f32_e32 v68, v68
	v_add_f32_e32 v70, 1.0, v70
	v_add_f32_e32 v71, 1.0, v71
	v_add_f32_e32 v72, 1.0, v72
	v_add_f32_e32 v73, 1.0, v73
	v_rcp_f32_e32 v69, v66
	v_add_f32_e32 v66, 1.0, v67
	v_rcp_f32_e32 v70, v70
	v_rcp_f32_e32 v71, v71
	v_rcp_f32_e32 v72, v72
	v_rcp_f32_e32 v73, v73
	v_rcp_f32_e32 v75, v66
	v_add_f32_e32 v66, 1.0, v68
	v_rcp_f32_e32 v76, v66
	v_cvt_pk_bf16_f32 v66, v70, v71
	v_cvt_pk_bf16_f32 v67, v72, v73
	v_cvt_pk_bf16_f32 v68, v74, v69
	v_mul_f32_e32 v58, 0xbfb8aa3b, v58
; __device__ __forceinline__ unsigned pk2_(float lo, float hi) { f32x2_t v = {lo, hi}; bf16x2_t b = __builtin_convertvector(v, bf16x2_t); return __builtin_bit_cast(unsigned, b); }
; __device__ __forceinline__ float sigm(float x) { return __builtin_amdgcn_rcpf(1.0f + __expf(-x)); }
; __device__ __forceinline__ void store16_wt(void* p, u32x4 v) { asm volatile("global_store_dwordx4 %0, %1, off sc1\n\ts_nop 1" :: "v"(p), "v"(v) : "memory"); }
; __device__ __forceinline__ float sigm(float x) { return __builtin_amdgcn_rcpf(1.0f + __expf(-x)); }
;     __device__ __forceinline__ void operator()(const f32x4 (&acc)[2][2][4][2], const Unit& u, int wr, int wc, int fr, int fq) const {
;         const int c0 = wc * 32 + 8 * fq;
; #pragma unroll
;         for (int ai = 0; ai < 2; ++ai)
; #pragma unroll
;             for (int m = 0; m < 4; ++m) { bf16_t* rowp = gm.at(u.pm, wr * 64 + fr + ai * HALF + m * 16, u.pn, c0);
; #pragma unroll
;                 for (int bj = 0; bj < 2; ++bj) { const f32x4 v0 = acc[ai][bj][m][0], v1 = acc[ai][bj][m][1];
;                     u32x4 w; w.x = pk2_(sigm(v0[0]), sigm(v0[1])); w.y = pk2_(sigm(v0[2]), sigm(v0[3])); w.z = pk2_(sigm(v1[0]), sigm(v1[1])); w.w = pk2_(sigm(v1[2]), sigm(v1[3]));
;                     store16_wt(rowp + bj * HALF, w); } }
;     }
	v_cvt_pk_bf16_f32 v69, v75, v76
	v_lshl_add_u64 v[70:71], v[78:79], 0, s[64:65]
	global_store_dwordx4 v[70:71], v[66:69], off
	s_nop 1
	v_add_u32_e32 v68, s13, v148
	v_mov_b64_e32 v[66:67], s[84:85]
	v_mul_f32_e32 v62, 0xbfb8aa3b, v62
	v_exp_f32_e32 v58, v58
	v_mul_f32_e32 v59, 0xbfb8aa3b, v59
	v_mad_i64_i32 v[66:67], s[12:13], s12, v68, v[66:67]
	v_exp_f32_e32 v68, v62
	v_exp_f32_e32 v59, v59
	v_lshl_add_u64 v[66:67], v[66:67], 0, s[14:15]
	v_mul_f32_e32 v62, 0xbfb8aa3b, v63
	v_add_f32_e32 v58, 1.0, v58
	v_exp_f32_e32 v69, v62
	v_lshl_add_u64 v[62:63], v[66:67], 0, v[142:143]
	v_add_f32_e32 v66, 1.0, v68
	v_rcp_f32_e32 v68, v58
	v_add_f32_e32 v58, 1.0, v59
	v_mul_f32_e32 v59, 0xbfb8aa3b, v60
	v_mul_f32_e32 v64, 0xbfb8aa3b, v64
	v_mul_f32_e32 v65, 0xbfb8aa3b, v65
	v_exp_f32_e32 v59, v59
	v_mul_f32_e32 v60, 0xbfb8aa3b, v61
	v_exp_f32_e32 v64, v64
	v_exp_f32_e32 v65, v65
	v_exp_f32_e32 v60, v60
	v_add_f32_e32 v67, 1.0, v69
	v_rcp_f32_e32 v61, v58
	v_add_f32_e32 v58, 1.0, v59
	v_mul_f32_e32 v50, 0xbfb8aa3b, v50
	v_rcp_f32_e32 v66, v66
	v_rcp_f32_e32 v67, v67
	v_add_f32_e32 v64, 1.0, v64
	v_add_f32_e32 v65, 1.0, v65
	v_rcp_f32_e32 v69, v58
	v_add_f32_e32 v58, 1.0, v60
	v_exp_f32_e32 v50, v50
	v_mul_f32_e32 v51, 0xbfb8aa3b, v51
	v_rcp_f32_e32 v64, v64
	v_rcp_f32_e32 v65, v65
	v_rcp_f32_e32 v70, v58
	v_exp_f32_e32 v51, v51
	v_cvt_pk_bf16_f32 v58, v66, v67
	v_add_f32_e32 v50, 1.0, v50
	v_cvt_pk_bf16_f32 v59, v64, v65
	v_cvt_pk_bf16_f32 v60, v68, v61
	v_cvt_pk_bf16_f32 v61, v69, v70
	global_store_dwordx4 v[62:63], v[58:61], off
	s_nop 1
	v_rcp_f32_e32 v58, v50
	v_add_f32_e32 v50, 1.0, v51
	v_mul_f32_e32 v51, 0xbfb8aa3b, v52
	v_mul_f32_e32 v54, 0xbfb8aa3b, v54
	v_mul_f32_e32 v55, 0xbfb8aa3b, v55
	v_mul_f32_e32 v56, 0xbfb8aa3b, v56
	v_mul_f32_e32 v57, 0xbfb8aa3b, v57
	v_exp_f32_e32 v51, v51
	v_mul_f32_e32 v52, 0xbfb8aa3b, v53
	v_exp_f32_e32 v54, v54
	v_exp_f32_e32 v55, v55
	v_exp_f32_e32 v56, v56
	v_exp_f32_e32 v57, v57
	v_exp_f32_e32 v52, v52
	v_rcp_f32_e32 v53, v50
	v_add_f32_e32 v50, 1.0, v51
	v_add_f32_e32 v54, 1.0, v54
	v_add_f32_e32 v55, 1.0, v55
	v_add_f32_e32 v56, 1.0, v56
	v_add_f32_e32 v57, 1.0, v57
	v_rcp_f32_e32 v59, v50
	v_add_f32_e32 v50, 1.0, v52
	v_rcp_f32_e32 v54, v54
	v_rcp_f32_e32 v55, v55
	v_rcp_f32_e32 v56, v56
	v_rcp_f32_e32 v57, v57
	v_rcp_f32_e32 v60, v50
	v_cvt_pk_bf16_f32 v50, v54, v55
	v_cvt_pk_bf16_f32 v52, v58, v53
	v_cvt_pk_bf16_f32 v51, v56, v57
	v_cvt_pk_bf16_f32 v53, v59, v60
	v_lshl_add_u64 v[54:55], v[62:63], 0, s[64:65]
	global_store_dwordx4 v[54:55], v[50:53], off
	s_nop 1
	s_mov_b64 s[12:13], 0x1800
	s_and_b64 vcc, exec, s[36:37]
	s_mov_b32 s13, s11
	s_mov_b64 s[14:15], 0x1800
	s_mov_b64 s[74:75], s[4:5]
	s_mov_b64 s[76:77], s[68:69]
	s_cbranch_vccnz .LBB0_1149
	s_mov_b64 s[14:15], 0x4200
	s_mov_b32 s13, s9
	s_mov_b64 s[74:75], s[18:19]
	s_mov_b64 s[76:77], s[46:47]
.LBB0_1149:
	v_mul_f32_e32 v42, 0xbfb8aa3b, v42
	v_add_u32_e32 v52, s13, v149
	v_mov_b64_e32 v[50:51], s[74:75]
	v_mul_f32_e32 v46, 0xbfb8aa3b, v46
	v_exp_f32_e32 v42, v42
	v_mul_f32_e32 v43, 0xbfb8aa3b, v43
	v_mad_i64_i32 v[50:51], s[74:75], s14, v52, v[50:51]
	v_exp_f32_e32 v52, v46
	v_exp_f32_e32 v43, v43
	s_lshl_b64 vcc, s[76:77], 1
	v_lshl_add_u64 v[50:51], v[50:51], 0, vcc
	v_mul_f32_e32 v46, 0xbfb8aa3b, v47
	v_add_f32_e32 v42, 1.0, v42
	v_exp_f32_e32 v53, v46
	v_lshl_add_u64 v[46:47], v[50:51], 0, v[142:143]
	v_add_f32_e32 v50, 1.0, v52
	v_rcp_f32_e32 v52, v42
	v_add_f32_e32 v42, 1.0, v43
	v_mul_f32_e32 v43, 0xbfb8aa3b, v44
	v_mul_f32_e32 v48, 0xbfb8aa3b, v48
	v_mul_f32_e32 v49, 0xbfb8aa3b, v49
	v_exp_f32_e32 v43, v43
	v_mul_f32_e32 v44, 0xbfb8aa3b, v45
	v_exp_f32_e32 v48, v48
	v_exp_f32_e32 v49, v49
	v_exp_f32_e32 v44, v44
	v_add_f32_e32 v51, 1.0, v53
	v_rcp_f32_e32 v45, v42
	v_add_f32_e32 v42, 1.0, v43
	v_mul_f32_e32 v34, 0xbfb8aa3b, v34
	v_rcp_f32_e32 v50, v50
	v_rcp_f32_e32 v51, v51
	v_add_f32_e32 v48, 1.0, v48
	v_add_f32_e32 v49, 1.0, v49
	v_rcp_f32_e32 v53, v42
	v_add_f32_e32 v42, 1.0, v44
	v_exp_f32_e32 v34, v34
	v_mul_f32_e32 v35, 0xbfb8aa3b, v35
	v_rcp_f32_e32 v48, v48
	v_rcp_f32_e32 v49, v49
	v_rcp_f32_e32 v54, v42
	v_exp_f32_e32 v35, v35
	v_cvt_pk_bf16_f32 v42, v50, v51
	v_add_f32_e32 v34, 1.0, v34
	v_cvt_pk_bf16_f32 v43, v48, v49
	v_cvt_pk_bf16_f32 v44, v52, v45
	v_cvt_pk_bf16_f32 v45, v53, v54
	v_mul_f32_e32 v38, 0xbfb8aa3b, v38
	v_mul_f32_e32 v39, 0xbfb8aa3b, v39
	global_store_dwordx4 v[46:47], v[42:45], off
	s_nop 1
	v_mul_f32_e32 v40, 0xbfb8aa3b, v40
	v_mul_f32_e32 v41, 0xbfb8aa3b, v41
	v_rcp_f32_e32 v42, v34
	v_add_f32_e32 v34, 1.0, v35
	v_mul_f32_e32 v35, 0xbfb8aa3b, v36
	v_exp_f32_e32 v38, v38
	v_exp_f32_e32 v39, v39
	v_exp_f32_e32 v40, v40
	v_exp_f32_e32 v41, v41
	v_exp_f32_e32 v35, v35
	v_mul_f32_e32 v36, 0xbfb8aa3b, v37
	v_exp_f32_e32 v36, v36
	v_add_f32_e32 v38, 1.0, v38
	v_add_f32_e32 v39, 1.0, v39
	v_add_f32_e32 v40, 1.0, v40
	v_add_f32_e32 v41, 1.0, v41
	v_rcp_f32_e32 v37, v34
	v_add_f32_e32 v34, 1.0, v35
	v_rcp_f32_e32 v38, v38
	v_rcp_f32_e32 v39, v39
	v_rcp_f32_e32 v40, v40
	v_rcp_f32_e32 v41, v41
	v_rcp_f32_e32 v43, v34
	v_add_f32_e32 v34, 1.0, v36
	v_rcp_f32_e32 v44, v34
	v_cvt_pk_bf16_f32 v34, v38, v39
	v_cvt_pk_bf16_f32 v35, v40, v41
	v_cvt_pk_bf16_f32 v36, v42, v37
	v_mul_f32_e32 v26, 0xbfb8aa3b, v26
; __device__ __forceinline__ unsigned pk2_(float lo, float hi) { f32x2_t v = {lo, hi}; bf16x2_t b = __builtin_convertvector(v, bf16x2_t); return __builtin_bit_cast(unsigned, b); }
; __device__ __forceinline__ float sigm(float x) { return __builtin_amdgcn_rcpf(1.0f + __expf(-x)); }
; __device__ __forceinline__ void store16_wt(void* p, u32x4 v) { asm volatile("global_store_dwordx4 %0, %1, off sc1\n\ts_nop 1" :: "v"(p), "v"(v) : "memory"); }
; __device__ __forceinline__ float sigm(float x) { return __builtin_amdgcn_rcpf(1.0f + __expf(-x)); }
;     __device__ __forceinline__ void operator()(const f32x4 (&acc)[2][2][4][2], const Unit& u, int wr, int wc, int fr, int fq) const {
;         const int c0 = wc * 32 + 8 * fq;
; #pragma unroll
;         for (int ai = 0; ai < 2; ++ai)
; #pragma unroll
;             for (int m = 0; m < 4; ++m) { bf16_t* rowp = gm.at(u.pm, wr * 64 + fr + ai * HALF + m * 16, u.pn, c0);
; #pragma unroll
;                 for (int bj = 0; bj < 2; ++bj) { const f32x4 v0 = acc[ai][bj][m][0], v1 = acc[ai][bj][m][1];
;                     u32x4 w; w.x = pk2_(sigm(v0[0]), sigm(v0[1])); w.y = pk2_(sigm(v0[2]), sigm(v0[3])); w.z = pk2_(sigm(v1[0]), sigm(v1[1])); w.w = pk2_(sigm(v1[2]), sigm(v1[3]));
;                     store16_wt(rowp + bj * HALF, w); } }
;     }
	v_cvt_pk_bf16_f32 v37, v43, v44
	v_lshl_add_u64 v[38:39], v[46:47], 0, s[64:65]
	global_store_dwordx4 v[38:39], v[34:37], off
	s_nop 1
	v_add_u32_e32 v36, s13, v150
	v_mov_b64_e32 v[34:35], s[84:85]
	v_mul_f32_e32 v30, 0xbfb8aa3b, v30
	v_exp_f32_e32 v26, v26
	v_mul_f32_e32 v27, 0xbfb8aa3b, v27
	v_mad_i64_i32 v[34:35], s[14:15], s14, v36, v[34:35]
	v_exp_f32_e32 v36, v30
	v_exp_f32_e32 v27, v27
	v_lshl_add_u64 v[34:35], v[34:35], 0, vcc
	v_mul_f32_e32 v30, 0xbfb8aa3b, v31
	v_add_f32_e32 v26, 1.0, v26
	v_exp_f32_e32 v37, v30
	v_lshl_add_u64 v[30:31], v[34:35], 0, v[142:143]
	v_add_f32_e32 v34, 1.0, v36
	v_rcp_f32_e32 v36, v26
	v_add_f32_e32 v26, 1.0, v27
	v_mul_f32_e32 v27, 0xbfb8aa3b, v28
	v_mul_f32_e32 v32, 0xbfb8aa3b, v32
	v_mul_f32_e32 v33, 0xbfb8aa3b, v33
	v_exp_f32_e32 v27, v27
	v_mul_f32_e32 v28, 0xbfb8aa3b, v29
	v_exp_f32_e32 v32, v32
	v_exp_f32_e32 v33, v33
	v_exp_f32_e32 v28, v28
	v_add_f32_e32 v35, 1.0, v37
	v_rcp_f32_e32 v29, v26
	v_add_f32_e32 v26, 1.0, v27
	v_mul_f32_e32 v18, 0xbfb8aa3b, v18
	v_rcp_f32_e32 v34, v34
	v_rcp_f32_e32 v35, v35
	v_add_f32_e32 v32, 1.0, v32
	v_add_f32_e32 v33, 1.0, v33
	v_rcp_f32_e32 v37, v26
	v_add_f32_e32 v26, 1.0, v28
	v_exp_f32_e32 v18, v18
	v_mul_f32_e32 v19, 0xbfb8aa3b, v19
	v_rcp_f32_e32 v32, v32
	v_rcp_f32_e32 v33, v33
	v_rcp_f32_e32 v38, v26
	v_exp_f32_e32 v19, v19
	v_cvt_pk_bf16_f32 v26, v34, v35
	v_add_f32_e32 v18, 1.0, v18
	v_cvt_pk_bf16_f32 v27, v32, v33
	v_cvt_pk_bf16_f32 v28, v36, v29
	v_cvt_pk_bf16_f32 v29, v37, v38
	global_store_dwordx4 v[30:31], v[26:29], off
	s_nop 1
	v_rcp_f32_e32 v26, v18
	v_add_f32_e32 v18, 1.0, v19
	v_mul_f32_e32 v19, 0xbfb8aa3b, v20
	v_mul_f32_e32 v22, 0xbfb8aa3b, v22
	v_mul_f32_e32 v23, 0xbfb8aa3b, v23
	v_mul_f32_e32 v24, 0xbfb8aa3b, v24
	v_mul_f32_e32 v25, 0xbfb8aa3b, v25
	v_exp_f32_e32 v19, v19
	v_mul_f32_e32 v20, 0xbfb8aa3b, v21
	v_exp_f32_e32 v22, v22
	v_exp_f32_e32 v23, v23
	v_exp_f32_e32 v24, v24
	v_exp_f32_e32 v25, v25
	v_exp_f32_e32 v20, v20
	v_rcp_f32_e32 v21, v18
	v_add_f32_e32 v18, 1.0, v19
	v_add_f32_e32 v22, 1.0, v22
	v_add_f32_e32 v23, 1.0, v23
	v_add_f32_e32 v24, 1.0, v24
	v_add_f32_e32 v25, 1.0, v25
	v_rcp_f32_e32 v27, v18
	v_add_f32_e32 v18, 1.0, v20
	v_rcp_f32_e32 v22, v22
	v_rcp_f32_e32 v23, v23
	v_rcp_f32_e32 v24, v24
	v_rcp_f32_e32 v25, v25
	v_rcp_f32_e32 v28, v18
	v_cvt_pk_bf16_f32 v18, v22, v23
	v_cvt_pk_bf16_f32 v20, v26, v21
	v_cvt_pk_bf16_f32 v19, v24, v25
	v_cvt_pk_bf16_f32 v21, v27, v28
	v_lshl_add_u64 v[22:23], v[30:31], 0, s[64:65]
	global_store_dwordx4 v[22:23], v[18:21], off
	s_nop 1
	s_and_b64 vcc, exec, s[36:37]
	s_cbranch_vccnz .LBB0_1151
	s_mov_b64 s[12:13], 0x4200
	s_mov_b32 s11, s9
	s_mov_b64 s[4:5], s[18:19]
	s_mov_b64 s[68:69], s[46:47]
.LBB0_1151:
	v_mul_f32_e32 v8, 0xbfb8aa3b, v8
	v_add_u32_e32 v20, s11, v151
	v_mov_b64_e32 v[18:19], s[4:5]
	v_mul_f32_e32 v12, 0xbfb8aa3b, v12
	v_exp_f32_e32 v8, v8
	v_mul_f32_e32 v9, 0xbfb8aa3b, v9
	v_mad_i64_i32 v[18:19], s[4:5], s12, v20, v[18:19]
	v_exp_f32_e32 v20, v12
	v_exp_f32_e32 v9, v9
	v_lshl_add_u64 v[18:19], s[68:69], 1, v[18:19]
	v_mov_b32_e32 v143, v16
	v_mul_f32_e32 v12, 0xbfb8aa3b, v13
	v_add_f32_e32 v8, 1.0, v8
	v_exp_f32_e32 v21, v12
	v_lshl_add_u64 v[12:13], v[18:19], 0, v[142:143]
	v_add_f32_e32 v18, 1.0, v20
	v_rcp_f32_e32 v20, v8
	v_add_f32_e32 v8, 1.0, v9
	v_mul_f32_e32 v9, 0xbfb8aa3b, v10
	v_mul_f32_e32 v14, 0xbfb8aa3b, v14
	v_mul_f32_e32 v15, 0xbfb8aa3b, v15
	v_exp_f32_e32 v9, v9
	v_mul_f32_e32 v10, 0xbfb8aa3b, v11
	v_exp_f32_e32 v14, v14
	v_exp_f32_e32 v15, v15
	v_exp_f32_e32 v10, v10
	v_add_f32_e32 v19, 1.0, v21
	v_rcp_f32_e32 v11, v8
	v_add_f32_e32 v8, 1.0, v9
	v_mul_f32_e32 v0, 0xbfb8aa3b, v0
	v_rcp_f32_e32 v18, v18
	v_rcp_f32_e32 v19, v19
	v_add_f32_e32 v14, 1.0, v14
	v_add_f32_e32 v15, 1.0, v15
	v_rcp_f32_e32 v21, v8
	v_add_f32_e32 v8, 1.0, v10
	v_exp_f32_e32 v0, v0
	v_mul_f32_e32 v1, 0xbfb8aa3b, v1
	v_rcp_f32_e32 v14, v14
	v_rcp_f32_e32 v15, v15
	v_rcp_f32_e32 v22, v8
	v_exp_f32_e32 v1, v1
	v_cvt_pk_bf16_f32 v8, v18, v19
	v_add_f32_e32 v0, 1.0, v0
	v_cvt_pk_bf16_f32 v9, v14, v15
	v_cvt_pk_bf16_f32 v10, v20, v11
	v_cvt_pk_bf16_f32 v11, v21, v22
	global_store_dwordx4 v[12:13], v[8:11], off
	s_nop 1
	v_rcp_f32_e32 v8, v0
	v_add_f32_e32 v0, 1.0, v1
	v_mul_f32_e32 v1, 0xbfb8aa3b, v2
	v_mul_f32_e32 v4, 0xbfb8aa3b, v4
	v_mul_f32_e32 v5, 0xbfb8aa3b, v5
	v_mul_f32_e32 v6, 0xbfb8aa3b, v6
	v_mul_f32_e32 v7, 0xbfb8aa3b, v7
	v_exp_f32_e32 v1, v1
	v_mul_f32_e32 v2, 0xbfb8aa3b, v3
	v_exp_f32_e32 v4, v4
	v_exp_f32_e32 v5, v5
	v_exp_f32_e32 v6, v6
	v_exp_f32_e32 v7, v7
	v_exp_f32_e32 v2, v2
	v_rcp_f32_e32 v3, v0
	v_add_f32_e32 v0, 1.0, v1
	v_add_f32_e32 v4, 1.0, v4
	v_add_f32_e32 v5, 1.0, v5
	v_add_f32_e32 v6, 1.0, v6
	v_add_f32_e32 v7, 1.0, v7
	v_rcp_f32_e32 v9, v0
	v_add_f32_e32 v0, 1.0, v2
	v_rcp_f32_e32 v4, v4
	v_rcp_f32_e32 v5, v5
	v_rcp_f32_e32 v6, v6
	v_rcp_f32_e32 v7, v7
	v_rcp_f32_e32 v10, v0
	v_cvt_pk_bf16_f32 v0, v4, v5
	v_cvt_pk_bf16_f32 v2, v8, v3
	v_cvt_pk_bf16_f32 v1, v6, v7
	v_cvt_pk_bf16_f32 v3, v9, v10
	v_lshl_add_u64 v[4:5], v[12:13], 0, s[64:65]
	global_store_dwordx4 v[4:5], v[0:3], off
	s_nop 1
	s_andn2_b64 vcc, exec, s[40:41]
	s_mov_b64 s[4:5], -1
	s_cbranch_vccnz .LBB0_1136
	s_andn2_b64 vcc, exec, s[38:39]
	s_cbranch_vccnz .LBB0_1135
	s_barrier
	s_branch .LBB0_1135

; __device__ __forceinline__ unsigned pk2_(float lo, float hi) { f32x2_t v = {lo, hi}; bf16x2_t b = __builtin_convertvector(v, bf16x2_t); return __builtin_bit_cast(unsigned, b); }
; __device__ __forceinline__ float sigm(float x) { return __builtin_amdgcn_rcpf(1.0f + __expf(-x)); }
; __device__ __forceinline__ void store16_wt(void* p, u32x4 v) { asm volatile("global_store_dwordx4 %0, %1, off sc1\n\ts_nop 1" :: "v"(p), "v"(v) : "memory"); }
; __device__ __forceinline__ float sigm(float x) { return __builtin_amdgcn_rcpf(1.0f + __expf(-x)); }
;     __device__ __forceinline__ void operator()(const f32x4 (&acc)[2][2][4][2], const Unit& u, int wr, int wc, int fr, int fq) const {
;         const int row0 = (local ? u.lpm : u.pm) * BM + wr * 64 + fr; const int col0 = u.pn * BM + wc * 32 + 8 * fq;
; #pragma unroll
;         for (int ai = 0; ai < 2; ++ai)
; #pragma unroll
;             for (int m = 0; m < 4; ++m) { bf16_t* rowp = O + (size_t)(row0 + ai * HALF + m * 16) * ldc + col0;
; #pragma unroll
;                 for (int bj = 0; bj < 2; ++bj) { f32x4 v0 = acc[ai][bj][m][0], v1 = acc[ai][bj][m][1];
;                     if (ACT == 1) { v0 = (f32x4){sigm(v0[0]), sigm(v0[1]), sigm(v0[2]), sigm(v0[3])}; v1 = (f32x4){sigm(v1[0]), sigm(v1[1]), sigm(v1[2]), sigm(v1[3])}; }
;                     u32x4 w; w.x = pk2_(v0[0], v0[1]); w.y = pk2_(v0[2], v0[3]); w.z = pk2_(v1[0], v1[1]); w.w = pk2_(v1[2], v1[3]);
;                     store16_wt(rowp + bj * HALF, w); } }
;     }
.LBB0_1509:
	v_lshl_or_b32 v146, s79, 8, v143
	v_lshl_add_u32 v145, s78, 8, v17
	v_ashrrev_i32_e32 v147, 31, v146
	v_mov_b64_e32 v[148:149], s[6:7]
	v_mad_i64_i32 v[150:151], s[12:13], v145, s24, v[148:149]
	v_lshlrev_b64 v[146:147], 1, v[146:147]
	v_lshl_add_u64 v[150:151], v[150:151], 0, v[146:147]
	v_cvt_pk_bf16_f32 v126, v126, v127
	v_cvt_pk_bf16_f32 v127, v128, v129
	v_cvt_pk_bf16_f32 v128, v122, v123
	v_cvt_pk_bf16_f32 v129, v124, v125
	global_store_dwordx4 v[150:151], v[126:129], off
	s_nop 1
	v_cvt_pk_bf16_f32 v110, v110, v111
	v_cvt_pk_bf16_f32 v111, v112, v113
	v_cvt_pk_bf16_f32 v112, v106, v107
	v_lshl_add_u64 v[106:107], v[150:151], 0, s[64:65]
	v_cvt_pk_bf16_f32 v113, v108, v109
	global_store_dwordx4 v[106:107], v[110:113], off
	s_nop 1
	v_or_b32_e32 v106, 16, v145
	v_mad_i64_i32 v[106:107], s[12:13], v106, s24, v[148:149]
	v_lshl_add_u64 v[110:111], v[106:107], 0, v[146:147]
	v_cvt_pk_bf16_f32 v106, v118, v119
	v_cvt_pk_bf16_f32 v107, v120, v121
	v_cvt_pk_bf16_f32 v108, v114, v115
	v_cvt_pk_bf16_f32 v109, v116, v117
	global_store_dwordx4 v[110:111], v[106:109], off
	s_nop 1
	v_cvt_pk_bf16_f32 v94, v94, v95
	v_cvt_pk_bf16_f32 v95, v96, v97
	v_cvt_pk_bf16_f32 v96, v90, v91
	v_lshl_add_u64 v[90:91], v[110:111], 0, s[64:65]
	v_cvt_pk_bf16_f32 v97, v92, v93
	global_store_dwordx4 v[90:91], v[94:97], off
	s_nop 1
	v_or_b32_e32 v90, 32, v145
	v_mad_i64_i32 v[90:91], s[12:13], v90, s24, v[148:149]
	v_lshl_add_u64 v[94:95], v[90:91], 0, v[146:147]
	v_cvt_pk_bf16_f32 v90, v102, v103
	v_cvt_pk_bf16_f32 v91, v104, v105
	v_cvt_pk_bf16_f32 v92, v98, v99
	v_cvt_pk_bf16_f32 v93, v100, v101
	global_store_dwordx4 v[94:95], v[90:93], off
	s_nop 1
	v_cvt_pk_bf16_f32 v78, v78, v79
	v_cvt_pk_bf16_f32 v79, v80, v81
	v_cvt_pk_bf16_f32 v80, v74, v75
	v_lshl_add_u64 v[74:75], v[94:95], 0, s[64:65]
	v_cvt_pk_bf16_f32 v81, v76, v77
	global_store_dwordx4 v[74:75], v[78:81], off
	s_nop 1
	v_or_b32_e32 v74, 48, v145
	v_mad_i64_i32 v[74:75], s[12:13], v74, s24, v[148:149]
	v_lshl_add_u64 v[78:79], v[74:75], 0, v[146:147]
	v_cvt_pk_bf16_f32 v74, v86, v87
	v_cvt_pk_bf16_f32 v75, v88, v89
	v_cvt_pk_bf16_f32 v76, v82, v83
	v_cvt_pk_bf16_f32 v77, v84, v85
	global_store_dwordx4 v[78:79], v[74:77], off
	s_nop 1
	v_cvt_pk_bf16_f32 v70, v70, v71
	v_cvt_pk_bf16_f32 v71, v72, v73
	v_cvt_pk_bf16_f32 v72, v66, v67
	v_lshl_add_u64 v[66:67], v[78:79], 0, s[64:65]
	v_cvt_pk_bf16_f32 v73, v68, v69
	global_store_dwordx4 v[66:67], v[70:73], off
	s_nop 1
	v_add_u32_e32 v66, 0x80, v145
	v_mad_i64_i32 v[66:67], s[12:13], v66, s24, v[148:149]
	v_lshl_add_u64 v[66:67], v[66:67], 0, v[146:147]
	v_cvt_pk_bf16_f32 v62, v62, v63
	v_cvt_pk_bf16_f32 v63, v64, v65
	v_cvt_pk_bf16_f32 v64, v58, v59
	v_cvt_pk_bf16_f32 v65, v60, v61
	global_store_dwordx4 v[66:67], v[62:65], off
	s_nop 1
	v_cvt_pk_bf16_f32 v46, v46, v47
	v_cvt_pk_bf16_f32 v47, v48, v49
	v_cvt_pk_bf16_f32 v48, v42, v43
	v_lshl_add_u64 v[42:43], v[66:67], 0, s[64:65]
	v_cvt_pk_bf16_f32 v49, v44, v45
	global_store_dwordx4 v[42:43], v[46:49], off
	s_nop 1
	v_add_u32_e32 v42, 0x90, v145
	v_mad_i64_i32 v[42:43], s[12:13], v42, s24, v[148:149]
	v_lshl_add_u64 v[46:47], v[42:43], 0, v[146:147]
	v_cvt_pk_bf16_f32 v42, v54, v55
	v_cvt_pk_bf16_f32 v43, v56, v57
	v_cvt_pk_bf16_f32 v44, v50, v51
	v_cvt_pk_bf16_f32 v45, v52, v53
	global_store_dwordx4 v[46:47], v[42:45], off
	s_nop 1
	v_cvt_pk_bf16_f32 v30, v30, v31
	v_cvt_pk_bf16_f32 v31, v32, v33
	v_cvt_pk_bf16_f32 v32, v26, v27
	v_lshl_add_u64 v[26:27], v[46:47], 0, s[64:65]
	v_cvt_pk_bf16_f32 v33, v28, v29
	global_store_dwordx4 v[26:27], v[30:33], off
	s_nop 1
	v_add_u32_e32 v26, 0xa0, v145
	v_mad_i64_i32 v[26:27], s[12:13], v26, s24, v[148:149]
	v_lshl_add_u64 v[30:31], v[26:27], 0, v[146:147]
	v_cvt_pk_bf16_f32 v26, v38, v39
	v_cvt_pk_bf16_f32 v27, v40, v41
	v_cvt_pk_bf16_f32 v28, v34, v35
	v_cvt_pk_bf16_f32 v29, v36, v37
	global_store_dwordx4 v[30:31], v[26:29], off
	s_nop 1
	v_cvt_pk_bf16_f32 v12, v12, v13
	v_cvt_pk_bf16_f32 v13, v14, v15
	v_cvt_pk_bf16_f32 v14, v8, v9
	v_lshl_add_u64 v[8:9], v[30:31], 0, s[64:65]
	v_cvt_pk_bf16_f32 v15, v10, v11
	global_store_dwordx4 v[8:9], v[12:15], off
	s_nop 1
	v_add_u32_e32 v8, 0xb0, v145
	v_mad_i64_i32 v[8:9], s[12:13], v8, s24, v[148:149]
	v_lshl_add_u64 v[12:13], v[8:9], 0, v[146:147]
	v_cvt_pk_bf16_f32 v8, v22, v23
	v_cvt_pk_bf16_f32 v9, v24, v25
	v_cvt_pk_bf16_f32 v10, v18, v19
	v_cvt_pk_bf16_f32 v11, v20, v21
	global_store_dwordx4 v[12:13], v[8:11], off
	s_nop 1
	v_cvt_pk_bf16_f32 v4, v4, v5
	v_cvt_pk_bf16_f32 v5, v6, v7
	v_cvt_pk_bf16_f32 v6, v0, v1
	v_cvt_pk_bf16_f32 v7, v2, v3
	v_lshl_add_u64 v[0:1], v[12:13], 0, s[64:65]
	global_store_dwordx4 v[0:1], v[4:7], off
	s_nop 1
	s_andn2_b64 vcc, exec, s[44:45]
	s_mov_b64 s[12:13], -1
	s_cbranch_vccnz .LBB0_1502
	s_andn2_b64 vcc, exec, s[4:5]
	s_cbranch_vccnz .LBB0_1501
	s_barrier
	s_branch .LBB0_1501
